# strategy 7.5: packed v_pk_add_f32 in the attention tile loops split into scalar v_add_f32 pairs (on top of v33)
# speedup vs baseline: 1.0059x; 1.0059x over previous
.LBB0_449:
	v_add_f32_e32 v101, v179, v164
	ds_read_b128 v[164:167], v168 offset:18528
	s_or_b64 s[4:5], s[6:7], s[4:5]
	v_add_f32_e32 v100, v178, v185
	s_or_b64 s[4:5], s[4:5], s[8:9]
	s_or_b64 s[4:5], s[4:5], s[10:11]
	v_add_f32_e32 v182, v100, v104
	v_add_f32_e32 v183, v101, v105
	s_xor_b32 s8, s48, 2
	v_exp_f32_e32 v64, v64
	v_exp_f32_e32 v65, v65
	s_nop 0
	v_add_f32_e32 v185, v65, v64
	v_cvt_pk_bf16_f32 v64, v64, v65
	v_mfma_f32_32x32x16_bf16 v[100:115], v[96:99], v[148:151], 0
	ds_read_b128 v[178:181], v168 offset:9280
	ds_read_b128 v[186:189], v168 offset:9312
	ds_read_b128 v[190:193], v168 offset:13888
	ds_read_b128 v[194:197], v168 offset:13920
	v_exp_f32_e32 v65, v66
	v_exp_f32_e32 v66, v67
	v_add_f32_e32 v67, v65, v185
	v_add_f32_e32 v67, v66, v67
	v_cvt_pk_bf16_f32 v65, v65, v66
	v_mfma_f32_32x32x16_bf16 v[100:115], v[92:95], v[152:155], v[100:115]
	v_exp_f32_e32 v66, v68
	v_exp_f32_e32 v68, v69
	v_add_f32_e32 v67, v66, v67
	v_cvt_pk_bf16_f32 v66, v66, v68
	v_add_f32_e32 v67, v68, v67
	v_mfma_f32_32x32x16_bf16 v[100:115], v[88:91], v[156:159], v[100:115]
	v_exp_f32_e32 v68, v70
	v_exp_f32_e32 v69, v71
	v_add_f32_e32 v70, v68, v67
	v_cvt_pk_bf16_f32 v67, v68, v69
	v_add_f32_e32 v68, v69, v70
	s_waitcnt lgkmcnt(4)
	v_mfma_f32_32x32x16_bf16 v[100:115], v[164:167], v[160:163], v[100:115]
	v_exp_f32_e32 v69, v72
	v_exp_f32_e32 v70, v73
	v_add_f32_e32 v71, v69, v68
	v_cvt_pk_bf16_f32 v68, v69, v70
	v_add_f32_e32 v69, v70, v71
	s_waitcnt lgkmcnt(0)
	v_mfma_f32_32x32x16_bf16 v[16:31], v[178:181], v[80:83], v[16:31]
	v_exp_f32_e32 v70, v74
	v_exp_f32_e32 v71, v75
	v_add_f32_e32 v72, v70, v69
	v_cvt_pk_bf16_f32 v69, v70, v71
	v_add_f32_e32 v70, v71, v72
	v_mfma_f32_32x32x16_bf16 v[16:31], v[186:189], v[84:87], v[16:31]
	v_exp_f32_e32 v71, v76
	v_exp_f32_e32 v72, v77
	v_add_f32_e32 v73, v71, v70
	v_cvt_pk_bf16_f32 v70, v71, v72
	v_add_f32_e32 v71, v72, v73
	v_mfma_f32_32x32x16_bf16 v[0:15], v[190:193], v[80:83], v[0:15]
	v_exp_f32_e32 v72, v78
	v_exp_f32_e32 v73, v79
	v_add_f32_e32 v74, v72, v71
	v_cvt_pk_bf16_f32 v71, v72, v73
	v_add_f32_e32 v198, v73, v74
	v_exp_f32_e32 v88, v100
	v_exp_f32_e32 v89, v101
	s_nop 0
	v_add_f32_e32 v165, v89, v88
	v_cvt_pk_bf16_f32 v164, v88, v89
	v_mfma_f32_32x32x16_bf16 v[0:15], v[194:197], v[84:87], v[0:15]
	ds_read_b128 v[72:75], v168 offset:23040
	ds_read_b128 v[76:79], v168 offset:23072
	ds_read_b128 v[80:83], v168 offset:23104
	v_cmp_nge_f32_e32 vcc, s62, v198
	ds_read_b128 v[84:87], v168 offset:23136
	v_exp_f32_e32 v166, v102
	v_exp_f32_e32 v167, v103
	s_waitcnt lgkmcnt(1)
	v_mfma_f32_32x32x16_bf16 v[88:103], v[72:75], v[116:119], 0
	ds_read_b128 v[178:181], v168 offset:27648
	ds_read_b128 v[186:189], v168 offset:27680
	ds_read_b128 v[190:193], v168 offset:32256
	ds_read_b128 v[194:197], v168 offset:32288
	v_add_f32_e32 v72, v166, v165
	v_add_f32_e32 v72, v167, v72
	v_cvt_pk_bf16_f32 v165, v166, v167
	v_mfma_f32_32x32x16_bf16 v[88:103], v[76:79], v[120:123], v[88:103]
	v_exp_f32_e32 v73, v104
	v_exp_f32_e32 v74, v105
	v_add_f32_e32 v72, v73, v72
	v_cvt_pk_bf16_f32 v166, v73, v74
	v_add_f32_e32 v72, v74, v72
	v_mfma_f32_32x32x16_bf16 v[88:103], v[80:83], v[124:127], v[88:103]
	v_exp_f32_e32 v73, v106
	v_exp_f32_e32 v74, v107
	v_add_f32_e32 v72, v73, v72
	v_cvt_pk_bf16_f32 v167, v73, v74
	v_add_f32_e32 v72, v74, v72
	s_waitcnt lgkmcnt(4)
	v_mfma_f32_32x32x16_bf16 v[88:103], v[84:87], v[128:131], v[88:103]
	v_exp_f32_e32 v73, v108
	v_exp_f32_e32 v74, v109
	v_add_f32_e32 v75, v73, v72
	v_cvt_pk_bf16_f32 v72, v73, v74
	v_add_f32_e32 v73, v74, v75
	s_waitcnt lgkmcnt(0)
	v_mfma_f32_32x32x16_bf16 v[48:63], v[178:181], v[64:67], v[48:63]
	v_exp_f32_e32 v74, v110
	v_exp_f32_e32 v75, v111
	v_add_f32_e32 v76, v74, v73
	v_cvt_pk_bf16_f32 v73, v74, v75
	v_add_f32_e32 v74, v75, v76
	v_mfma_f32_32x32x16_bf16 v[48:63], v[186:189], v[68:71], v[48:63]
	v_exp_f32_e32 v75, v112
	v_exp_f32_e32 v76, v113
	v_add_f32_e32 v77, v75, v74
	v_cvt_pk_bf16_f32 v74, v75, v76
	v_add_f32_e32 v75, v76, v77
	v_mfma_f32_32x32x16_bf16 v[32:47], v[190:193], v[64:67], v[32:47]
	v_exp_f32_e32 v76, v114
	v_exp_f32_e32 v77, v115
	v_add_f32_e32 v78, v76, v75
	v_cvt_pk_bf16_f32 v75, v76, v77
	v_add_f32_e32 v199, v77, v78
	v_exp_f32_e32 v76, v88
	v_exp_f32_e32 v77, v89
	s_nop 0
	v_add_f32_e32 v113, v77, v76
	v_cvt_pk_bf16_f32 v112, v76, v77
	v_mfma_f32_32x32x16_bf16 v[32:47], v[194:197], v[68:71], v[32:47]
	ds_read_b128 v[64:67], v168 offset:23040
	ds_read_b128 v[104:107], v168 offset:23072
	ds_read_b128 v[108:111], v168 offset:23104
	s_or_b64 s[6:7], s[4:5], vcc
	v_cmp_nge_f32_e32 vcc, s62, v199
	v_add_f32_e32 v182, v182, v198
	v_add_f32_e32 v183, v183, v199
	ds_read_b128 v[68:71], v168 offset:23136
	v_exp_f32_e32 v114, v90
	v_exp_f32_e32 v115, v91
	s_waitcnt lgkmcnt(1)
; #define LAS __attribute__((address_space(3)))
; template <int MODE, bool FAST> __device__ __forceinline__ bool attn_unit(LAS unsigned char* lds, const AttU& U, const int wv) {
;     ...
;     pb[1][0] = (bf16x8){0, 0, 0, 0, 0, 0, 0, 0}; pb[1][1] = pb[1][0];
;     ATT_QK(0, 0, 0);
;     bf16x8 kpre[NPRE > 0 ? NPRE : 1];
; #pragma unroll
;     for (int i_ = 0; i_ < NPRE; ++i_) kpre[i_] = *(LAS const bf16x8*)(lds + koff + i_ * 32);
	v_mfma_f32_32x32x16_bf16 v[76:91], v[64:67], v[148:151], 0
	ds_read_b128 v[178:181], v168 offset:27648
	ds_read_b128 v[186:189], v168 offset:27680
	ds_read_b128 v[190:193], v168 offset:32256
	ds_read_b128 v[194:197], v168 offset:32288
	v_add_f32_e32 v64, v114, v113
	v_add_f32_e32 v64, v115, v64
	v_cvt_pk_bf16_f32 v113, v114, v115
	v_mfma_f32_32x32x16_bf16 v[76:91], v[104:107], v[152:155], v[76:91]
	v_exp_f32_e32 v65, v92
	v_exp_f32_e32 v66, v93
	v_add_f32_e32 v64, v65, v64
	v_cvt_pk_bf16_f32 v114, v65, v66
	v_add_f32_e32 v64, v66, v64
	v_mfma_f32_32x32x16_bf16 v[76:91], v[108:111], v[156:159], v[76:91]
	v_exp_f32_e32 v65, v94
	v_exp_f32_e32 v66, v95
	v_add_f32_e32 v64, v65, v64
	v_cvt_pk_bf16_f32 v115, v65, v66
	v_add_f32_e32 v64, v66, v64
	s_waitcnt lgkmcnt(4)
	v_mfma_f32_32x32x16_bf16 v[76:91], v[68:71], v[160:163], v[76:91]
	v_exp_f32_e32 v65, v96
	v_exp_f32_e32 v66, v97
	v_add_f32_e32 v64, v65, v64
	v_cvt_pk_bf16_f32 v92, v65, v66
	v_add_f32_e32 v64, v66, v64
	s_waitcnt lgkmcnt(0)
	v_mfma_f32_32x32x16_bf16 v[16:31], v[178:181], v[164:167], v[16:31]
	v_exp_f32_e32 v65, v98
	v_exp_f32_e32 v66, v99
	v_add_f32_e32 v64, v65, v64
	v_cvt_pk_bf16_f32 v93, v65, v66
	v_add_f32_e32 v64, v66, v64
	v_mfma_f32_32x32x16_bf16 v[16:31], v[186:189], v[72:75], v[16:31]
	v_exp_f32_e32 v65, v100
	v_exp_f32_e32 v66, v101
	v_add_f32_e32 v64, v65, v64
	v_cvt_pk_bf16_f32 v94, v65, v66
	v_add_f32_e32 v64, v66, v64
	v_mfma_f32_32x32x16_bf16 v[0:15], v[190:193], v[164:167], v[0:15]
	v_exp_f32_e32 v65, v102
	v_exp_f32_e32 v66, v103
	v_add_f32_e32 v64, v65, v64
	v_cvt_pk_bf16_f32 v95, v65, v66
	v_add_f32_e32 v198, v66, v64
	s_mulk_i32 s8, 0x4800
	v_exp_f32_e32 v68, v76
	v_exp_f32_e32 v69, v77
	s_nop 0
	v_add_f32_e32 v97, v69, v68
	v_cvt_pk_bf16_f32 v96, v68, v69
	v_mfma_f32_32x32x16_bf16 v[0:15], v[194:197], v[72:75], v[0:15]
	v_add_u32_e32 v185, s8, v184
	ds_read_b128 v[64:67], v185
	ds_read_b128 v[100:103], v185 offset:32
	ds_read_b128 v[104:107], v185 offset:64
	v_cmp_nge_f32_e64 s[4:5], s62, v198
	ds_read_b128 v[108:111], v185 offset:96
	s_or_b64 s[6:7], s[6:7], vcc
	v_exp_f32_e32 v98, v78
	v_exp_f32_e32 v99, v79
	s_waitcnt lgkmcnt(1)
	v_mfma_f32_32x32x16_bf16 v[64:79], v[64:67], v[116:119], 0
	ds_read_b128 v[164:167], v168 offset:27712
	ds_read_b128 v[178:181], v168 offset:27744
	ds_read_b128 v[186:189], v168 offset:32320
	ds_read_b128 v[190:193], v168 offset:32352
	v_add_f32_e32 v97, v98, v97
	v_add_f32_e32 v168, v99, v97
	v_cvt_pk_bf16_f32 v97, v98, v99
	v_mfma_f32_32x32x16_bf16 v[64:79], v[100:103], v[120:123], v[64:79]
	v_exp_f32_e32 v80, v80
	v_exp_f32_e32 v81, v81
	v_add_f32_e32 v99, v80, v168
	v_cvt_pk_bf16_f32 v98, v80, v81
	v_add_f32_e32 v80, v81, v99
	v_mfma_f32_32x32x16_bf16 v[64:79], v[104:107], v[124:127], v[64:79]
	v_exp_f32_e32 v81, v82
	v_exp_f32_e32 v82, v83
	v_add_f32_e32 v80, v81, v80
	v_cvt_pk_bf16_f32 v99, v81, v82
	v_add_f32_e32 v80, v82, v80
	s_waitcnt lgkmcnt(4)
	v_mfma_f32_32x32x16_bf16 v[64:79], v[108:111], v[128:131], v[64:79]
	v_exp_f32_e32 v81, v84
	v_exp_f32_e32 v82, v85
	v_add_f32_e32 v80, v81, v80
	v_cvt_pk_bf16_f32 v100, v81, v82
	v_add_f32_e32 v80, v82, v80
	s_waitcnt lgkmcnt(0)
	v_mfma_f32_32x32x16_bf16 v[48:63], v[164:167], v[112:115], v[48:63]
	v_exp_f32_e32 v81, v86
	v_exp_f32_e32 v82, v87
	v_add_f32_e32 v80, v81, v80
	v_cvt_pk_bf16_f32 v101, v81, v82
	v_add_f32_e32 v80, v82, v80
	v_mfma_f32_32x32x16_bf16 v[48:63], v[178:181], v[92:95], v[48:63]
	v_exp_f32_e32 v81, v88
	v_exp_f32_e32 v82, v89
	v_add_f32_e32 v80, v81, v80
	v_cvt_pk_bf16_f32 v102, v81, v82
	v_add_f32_e32 v80, v82, v80
	v_mfma_f32_32x32x16_bf16 v[32:47], v[186:189], v[112:115], v[32:47]
	v_exp_f32_e32 v81, v90
	v_exp_f32_e32 v82, v91
	v_add_f32_e32 v80, v81, v80
	v_cvt_pk_bf16_f32 v103, v81, v82
	v_add_f32_e32 v199, v82, v80
	v_mfma_f32_32x32x16_bf16 v[32:47], v[190:193], v[92:95], v[32:47]
	ds_read_b128 v[80:83], v185
	ds_read_b128 v[108:111], v185 offset:32
	ds_read_b128 v[104:107], v185 offset:64
	s_or_b64 s[4:5], s[6:7], s[4:5]
	v_cmp_nge_f32_e32 vcc, s62, v199
	s_or_b64 s[4:5], s[4:5], vcc
	s_cmp_lg_u64 s[4:5], 0
	s_cselect_b64 s[4:5], -1, 0
	s_or_b64 s[42:43], s[42:43], s[4:5]
	v_add_f32_e32 v178, v182, v198
	v_add_f32_e32 v179, v183, v199
	s_waitcnt lgkmcnt(0)
	s_barrier
	s_add_u32 s46, s46, 0x8000
	s_addc_u32 s47, s47, 0
	s_and_b64 vcc, exec, s[44:45]
	s_cbranch_vccnz .LBB0_451
	s_mov_b32 s33, s14
	s_branch .LBB0_437

.LBB0_935:
	s_or_b64 s[6:7], s[8:9], s[6:7]
	v_add_f32_e32 v84, v204, v246
	v_add_f32_e32 v85, v205, v247
	s_or_b64 s[6:7], s[6:7], s[10:11]
	s_or_b64 s[6:7], s[6:7], s[12:13]
	v_add_f32_e32 v178, v84, v210
	v_add_f32_e32 v179, v85, v211
	s_xor_b32 s10, s77, 2
	v_add_u32_e32 v222, s78, v244
	v_exp_f32_e32 v64, v64
	v_exp_f32_e32 v65, v65
	s_nop 0
	v_add_f32_e32 v84, v65, v64
	v_cvt_pk_bf16_f32 v166, v64, v65
	v_exp_f32_e32 v64, v66
	ds_read_b128 v[204:207], v199 offset:22624
	ds_read_b128 v[208:211], v199 offset:22656
	ds_read_b128 v[218:221], v199 offset:22688
	v_exp_f32_e32 v65, v67
	v_add_f32_e32 v66, v64, v84
	v_mfma_f32_32x32x16_bf16 v[80:95], v[80:83], v[122:125], 0
	v_add_f32_e32 v66, v65, v66
	v_cvt_pk_bf16_f32 v167, v64, v65
	v_mfma_f32_32x32x16_bf16 v[80:95], v[182:185], v[126:129], v[80:95]
	v_exp_f32_e32 v64, v68
	v_exp_f32_e32 v65, v69
	v_add_f32_e32 v66, v64, v66
	v_add_f32_e32 v66, v65, v66
	v_cvt_pk_bf16_f32 v168, v64, v65
	v_mfma_f32_32x32x16_bf16 v[80:95], v[174:177], v[130:133], v[80:95]
	v_exp_f32_e32 v64, v70
	v_exp_f32_e32 v65, v71
	v_add_f32_e32 v66, v64, v66
	v_add_f32_e32 v174, v65, v66
	v_cvt_pk_bf16_f32 v169, v64, v65
	s_waitcnt lgkmcnt(0)
	v_mfma_f32_32x32x16_bf16 v[80:95], v[204:207], v[134:137], v[80:95]
	ds_read_b128 v[64:67], v222 offset:13376
	ds_read_b128 v[68:71], v222 offset:13408
	ds_read_b128 v[180:183], v222 offset:17984
	ds_read_b128 v[222:225], v222 offset:18016
	v_exp_f32_e32 v72, v72
	v_exp_f32_e32 v73, v73
	v_add_f32_e32 v174, v72, v174
	v_add_f32_e32 v175, v73, v174
	v_cvt_pk_bf16_f32 v174, v72, v73
	v_mfma_f32_32x32x16_bf16 v[80:95], v[208:211], v[154:157], v[80:95]
	v_exp_f32_e32 v72, v74
	v_exp_f32_e32 v73, v75
	v_add_f32_e32 v74, v72, v175
	v_add_f32_e32 v74, v73, v74
	v_cvt_pk_bf16_f32 v175, v72, v73
	v_mfma_f32_32x32x16_bf16 v[80:95], v[218:221], v[158:161], v[80:95]
	v_exp_f32_e32 v72, v76
	v_exp_f32_e32 v73, v77
	v_add_f32_e32 v74, v72, v74
	v_add_f32_e32 v74, v73, v74
	v_cvt_pk_bf16_f32 v176, v72, v73
	s_waitcnt lgkmcnt(0)
	v_mfma_f32_32x32x16_bf16 v[16:31], v[64:67], v[162:165], v[16:31]
	v_exp_f32_e32 v64, v78
	v_exp_f32_e32 v65, v79
	v_add_f32_e32 v66, v64, v74
	v_add_f32_e32 v204, v65, v66
	v_cvt_pk_bf16_f32 v177, v64, v65
	v_mfma_f32_32x32x16_bf16 v[0:15], v[180:183], v[162:165], v[0:15]
	ds_read_b128 v[64:67], v199 offset:29184
	ds_read_b128 v[180:183], v199 offset:29216
	ds_read_b128 v[208:211], v199 offset:29248
	v_cmp_nge_f32_e32 vcc, s48, v204
	v_mfma_f32_32x32x16_bf16 v[16:31], v[68:71], v[170:173], v[16:31]
	v_mfma_f32_32x32x16_bf16 v[0:15], v[222:225], v[170:173], v[0:15]
	v_mad_u32_u24 v68, v187, s69, v186
	v_add_u32_e32 v206, s76, v68
	v_exp_f32_e32 v68, v80
	v_exp_f32_e32 v69, v81
	s_nop 0
	v_add_f32_e32 v70, v69, v68
	v_cvt_pk_bf16_f32 v162, v68, v69
	v_exp_f32_e32 v80, v82
	ds_read_b128 v[170:173], v199 offset:29280
	ds_read_b128 v[218:221], v199 offset:29312
	ds_read_b128 v[222:225], v199 offset:29344
	v_exp_f32_e32 v81, v83
	v_add_f32_e32 v82, v80, v70
	s_waitcnt lgkmcnt(3)
	v_mfma_f32_32x32x16_bf16 v[64:79], v[64:67], v[98:101], 0
	v_add_f32_e32 v82, v81, v82
	v_cvt_pk_bf16_f32 v163, v80, v81
	v_mfma_f32_32x32x16_bf16 v[64:79], v[180:183], v[102:105], v[64:79]
	v_exp_f32_e32 v80, v84
	v_exp_f32_e32 v81, v85
	v_add_f32_e32 v82, v80, v82
	v_add_f32_e32 v82, v81, v82
	v_cvt_pk_bf16_f32 v164, v80, v81
	v_mfma_f32_32x32x16_bf16 v[64:79], v[208:211], v[106:109], v[64:79]
	v_exp_f32_e32 v80, v86
	v_exp_f32_e32 v81, v87
	v_add_f32_e32 v82, v80, v82
	v_add_f32_e32 v184, v81, v82
	v_cvt_pk_bf16_f32 v165, v80, v81
	s_waitcnt lgkmcnt(0)
	v_mfma_f32_32x32x16_bf16 v[64:79], v[170:173], v[110:113], v[64:79]
	ds_read_b128 v[80:83], v206 offset:35840
	ds_read_b128 v[84:87], v206 offset:35872
	ds_read_b128 v[180:183], v206 offset:40448
	ds_read_b128 v[208:211], v206 offset:40480
	v_exp_f32_e32 v88, v88
	v_exp_f32_e32 v89, v89
	v_add_f32_e32 v170, v88, v184
	v_add_f32_e32 v171, v89, v170
	v_cvt_pk_bf16_f32 v170, v88, v89
	v_mfma_f32_32x32x16_bf16 v[64:79], v[218:221], v[114:117], v[64:79]
	v_exp_f32_e32 v88, v90
	v_exp_f32_e32 v89, v91
	v_add_f32_e32 v90, v88, v171
	v_add_f32_e32 v90, v89, v90
	v_cvt_pk_bf16_f32 v171, v88, v89
	v_mfma_f32_32x32x16_bf16 v[64:79], v[222:225], v[118:121], v[64:79]
	v_exp_f32_e32 v88, v92
	v_exp_f32_e32 v89, v93
	v_add_f32_e32 v90, v88, v90
	v_add_f32_e32 v90, v89, v90
	v_cvt_pk_bf16_f32 v172, v88, v89
	s_waitcnt lgkmcnt(0)
	v_mfma_f32_32x32x16_bf16 v[48:63], v[80:83], v[166:169], v[48:63]
	v_exp_f32_e32 v80, v94
	v_exp_f32_e32 v81, v95
	v_add_f32_e32 v82, v80, v90
	v_add_f32_e32 v205, v81, v82
	v_cvt_pk_bf16_f32 v173, v80, v81
	v_mfma_f32_32x32x16_bf16 v[32:47], v[180:183], v[166:169], v[32:47]
	ds_read_b128 v[80:83], v199 offset:29184
	ds_read_b128 v[166:169], v199 offset:29216
	ds_read_b128 v[182:185], v199 offset:29248
	s_or_b64 s[8:9], s[6:7], vcc
	v_cmp_nge_f32_e32 vcc, s48, v205
	v_add_f32_e32 v204, v178, v204
	v_add_f32_e32 v205, v179, v205
	v_mfma_f32_32x32x16_bf16 v[48:63], v[84:87], v[174:177], v[48:63]
	v_exp_f32_e32 v64, v64
	v_exp_f32_e32 v65, v65
	s_nop 0
	v_add_f32_e32 v84, v65, v64
	v_cvt_pk_bf16_f32 v178, v64, v65
	v_exp_f32_e32 v64, v66
	v_exp_f32_e32 v65, v67
	v_add_f32_e32 v66, v64, v84
	v_mfma_f32_32x32x16_bf16 v[32:47], v[208:211], v[174:177], v[32:47]
	ds_read_b128 v[174:177], v199 offset:29280
	ds_read_b128 v[208:211], v199 offset:29312
	ds_read_b128 v[218:221], v199 offset:29344
	s_waitcnt lgkmcnt(3)
; #define LAS __attribute__((address_space(3)))
; template <int MODE, bool FAST> __device__ __forceinline__ bool attn_unit(LAS unsigned char* lds, const AttU& U, const int wv) {
;     ...
;     pb[1][0] = (bf16x8){0, 0, 0, 0, 0, 0, 0, 0}; pb[1][1] = pb[1][0];
;     ATT_QK(0, 0, 0);
;     bf16x8 kpre[NPRE > 0 ? NPRE : 1];
; #pragma unroll
;     for (int i_ = 0; i_ < NPRE; ++i_) kpre[i_] = *(LAS const bf16x8*)(lds + koff + i_ * 32);
;     ...
;     if constexpr (FAST) {
;         for (int t2 = U.kt0; t2 < U.kt1; t2 += 2) { ATT_TILE(t2, 4, rk, rr, rv); ATT_TILE(t2 + 1, 4, rk2, rr2, rv2); }
	v_mfma_f32_32x32x16_bf16 v[80:95], v[80:83], v[122:125], 0
	v_add_f32_e32 v66, v65, v66
	v_cvt_pk_bf16_f32 v179, v64, v65
	v_mfma_f32_32x32x16_bf16 v[80:95], v[166:169], v[126:129], v[80:95]
	v_exp_f32_e32 v64, v68
	v_exp_f32_e32 v65, v69
	v_add_f32_e32 v66, v64, v66
	v_add_f32_e32 v66, v65, v66
	v_cvt_pk_bf16_f32 v180, v64, v65
	v_mfma_f32_32x32x16_bf16 v[80:95], v[182:185], v[130:133], v[80:95]
	v_exp_f32_e32 v64, v70
	v_exp_f32_e32 v65, v71
	v_add_f32_e32 v66, v64, v66
	v_add_f32_e32 v182, v65, v66
	v_cvt_pk_bf16_f32 v181, v64, v65
	s_waitcnt lgkmcnt(0)
	v_mfma_f32_32x32x16_bf16 v[80:95], v[174:177], v[134:137], v[80:95]
	ds_read_b128 v[64:67], v206 offset:35840
	ds_read_b128 v[68:71], v206 offset:35872
	ds_read_b128 v[166:169], v206 offset:40448
	ds_read_b128 v[222:225], v206 offset:40480
	v_exp_f32_e32 v72, v72
	v_exp_f32_e32 v73, v73
	v_add_f32_e32 v174, v72, v182
	v_add_f32_e32 v174, v73, v174
	v_cvt_pk_bf16_f32 v182, v72, v73
	v_mfma_f32_32x32x16_bf16 v[80:95], v[208:211], v[154:157], v[80:95]
	v_exp_f32_e32 v72, v74
	v_exp_f32_e32 v73, v75
	v_add_f32_e32 v74, v72, v174
	v_add_f32_e32 v74, v73, v74
	v_cvt_pk_bf16_f32 v183, v72, v73
	v_mfma_f32_32x32x16_bf16 v[80:95], v[218:221], v[158:161], v[80:95]
	v_exp_f32_e32 v72, v76
	v_exp_f32_e32 v73, v77
	v_add_f32_e32 v74, v72, v74
	v_add_f32_e32 v74, v73, v74
	v_cvt_pk_bf16_f32 v184, v72, v73
	s_waitcnt lgkmcnt(0)
	v_mfma_f32_32x32x16_bf16 v[16:31], v[64:67], v[162:165], v[16:31]
	v_exp_f32_e32 v64, v78
	v_exp_f32_e32 v65, v79
	v_add_f32_e32 v66, v64, v74
	v_add_f32_e32 v226, v65, v66
	v_cvt_pk_bf16_f32 v185, v64, v65
	v_mfma_f32_32x32x16_bf16 v[0:15], v[166:169], v[162:165], v[0:15]
	s_mulk_i32 s10, 0x5800
	v_add_u32_e32 v199, s10, v242
	ds_read_b128 v[64:67], v199
	ds_read_b128 v[164:167], v199 offset:32
	ds_read_b128 v[174:177], v199 offset:64
	v_cmp_nge_f32_e64 s[6:7], s48, v226
	v_mfma_f32_32x32x16_bf16 v[16:31], v[68:71], v[170:173], v[16:31]
	v_exp_f32_e32 v68, v80
	v_exp_f32_e32 v69, v81
	s_nop 0
	v_add_f32_e32 v70, v69, v68
	v_cvt_pk_bf16_f32 v162, v68, v69
	v_exp_f32_e32 v80, v82
	v_exp_f32_e32 v81, v83
	v_add_f32_e32 v82, v80, v70
	v_mfma_f32_32x32x16_bf16 v[0:15], v[222:225], v[170:173], v[0:15]
	s_or_b64 s[8:9], s[8:9], vcc
	ds_read_b128 v[168:171], v199 offset:96
	ds_read_b128 v[208:211], v199 offset:128
	ds_read_b128 v[218:221], v199 offset:160
	s_waitcnt lgkmcnt(3)
	v_mfma_f32_32x32x16_bf16 v[64:79], v[64:67], v[98:101], 0
	v_add_f32_e32 v82, v81, v82
	v_cvt_pk_bf16_f32 v163, v80, v81
	v_mfma_f32_32x32x16_bf16 v[64:79], v[164:167], v[102:105], v[64:79]
	v_exp_f32_e32 v80, v84
	v_exp_f32_e32 v81, v85
	v_add_f32_e32 v82, v80, v82
	v_add_f32_e32 v82, v81, v82
	v_cvt_pk_bf16_f32 v164, v80, v81
	v_mfma_f32_32x32x16_bf16 v[64:79], v[174:177], v[106:109], v[64:79]
	v_exp_f32_e32 v80, v86
	v_exp_f32_e32 v81, v87
	v_add_f32_e32 v82, v80, v82
	v_add_f32_e32 v166, v81, v82
	v_cvt_pk_bf16_f32 v165, v80, v81
	s_waitcnt lgkmcnt(0)
	v_mfma_f32_32x32x16_bf16 v[64:79], v[168:171], v[110:113], v[64:79]
	ds_read_b128 v[80:83], v206 offset:35904
	ds_read_b128 v[84:87], v206 offset:35936
	ds_read_b128 v[222:225], v206 offset:40512
	ds_read_b128 v[246:249], v206 offset:40544
	v_exp_f32_e32 v88, v88
	v_exp_f32_e32 v89, v89
	v_add_f32_e32 v166, v88, v166
	v_add_f32_e32 v167, v89, v166
	v_cvt_pk_bf16_f32 v166, v88, v89
	v_mfma_f32_32x32x16_bf16 v[64:79], v[208:211], v[114:117], v[64:79]
	v_exp_f32_e32 v88, v90
	v_exp_f32_e32 v89, v91
	v_add_f32_e32 v90, v88, v167
	v_add_f32_e32 v90, v89, v90
	v_cvt_pk_bf16_f32 v167, v88, v89
	v_mfma_f32_32x32x16_bf16 v[64:79], v[218:221], v[118:121], v[64:79]
	v_exp_f32_e32 v88, v92
	v_exp_f32_e32 v89, v93
	v_add_f32_e32 v90, v88, v90
	v_add_f32_e32 v90, v89, v90
	v_cvt_pk_bf16_f32 v168, v88, v89
	s_waitcnt lgkmcnt(0)
	v_mfma_f32_32x32x16_bf16 v[48:63], v[80:83], v[178:181], v[48:63]
	v_exp_f32_e32 v80, v94
	v_exp_f32_e32 v81, v95
	v_add_f32_e32 v82, v80, v90
	v_add_f32_e32 v227, v81, v82
	v_cvt_pk_bf16_f32 v169, v80, v81
	v_mfma_f32_32x32x16_bf16 v[32:47], v[222:225], v[178:181], v[32:47]
	ds_read_b128 v[80:83], v199
	ds_read_b128 v[174:177], v199 offset:32
	ds_read_b128 v[170:173], v199 offset:64
	s_or_b64 s[6:7], s[8:9], s[6:7]
	v_cmp_nge_f32_e32 vcc, s48, v227
	s_or_b64 s[6:7], s[6:7], vcc
	s_cmp_lg_u64 s[6:7], 0
	s_cselect_b64 s[6:7], -1, 0
	s_or_b64 s[42:43], s[42:43], s[6:7]
	v_mfma_f32_32x32x16_bf16 v[48:63], v[84:87], v[182:185], v[48:63]
	v_add_f32_e64 v204, v204, v226
	v_add_f32_e64 v205, v205, v227
	s_waitcnt lgkmcnt(0)
	s_barrier
	v_mfma_f32_32x32x16_bf16 v[32:47], v[246:249], v[182:185], v[32:47]
	s_add_u32 s40, s40, 0x40000
	s_mov_b64 s[6:7], 0x2000
	s_addc_u32 s41, s41, 0
	v_lshl_add_u64 v[202:203], v[202:203], 0, s[6:7]
	s_and_b64 vcc, exec, s[44:45]
	s_cbranch_vccnz .LBB0_937
	s_mov_b32 s61, s30
	s_branch .LBB0_923
